# IN loop static prio waves 0-3 plus OUT loop (layers 0-2) static prio waves 4-7, flips removed in both
# baseline (speedup 1.0000x reference)
.LBB0_501:
	s_add_u32 s62, s46, 0x100
	v_mov_b32_e32 v4, 0
	s_addc_u32 s63, s47, 0
	s_mov_b32 s64, -2
	s_waitcnt lgkmcnt(0)
	v_mov_b32_e32 v5, v4
	v_mov_b32_e32 v6, v4
	v_mov_b32_e32 v7, v4
	v_mov_b32_e32 v8, v4
	v_mov_b32_e32 v9, v4
	v_mov_b32_e32 v10, v4
	v_mov_b32_e32 v11, v4
	v_mov_b32_e32 v20, v4
	s_waitcnt vmcnt(0)
	v_mov_b32_e32 v21, v4
	v_mov_b32_e32 v22, v4
	v_mov_b32_e32 v23, v4
	v_mov_b32_e32 v24, v4
	v_mov_b32_e32 v25, v4
	v_mov_b32_e32 v26, v4
	v_mov_b32_e32 v27, v4
	v_mov_b32_e32 v36, v4
	v_mov_b32_e32 v37, v4
	v_mov_b32_e32 v38, v4
	v_mov_b32_e32 v39, v4
	v_mov_b32_e32 v40, v4
	v_mov_b32_e32 v41, v4
	v_mov_b32_e32 v42, v4
	v_mov_b32_e32 v43, v4
	v_mov_b32_e32 v52, v4
	v_mov_b32_e32 v53, v4
	v_mov_b32_e32 v54, v4
	v_mov_b32_e32 v55, v4
	v_mov_b32_e32 v56, v4
	v_mov_b32_e32 v57, v4
	v_mov_b32_e32 v58, v4
	v_mov_b32_e32 v59, v4
	v_mov_b32_e32 v12, v4
	v_mov_b32_e32 v13, v4
	v_mov_b32_e32 v14, v4
	v_mov_b32_e32 v15, v4
	v_mov_b32_e32 v16, v4
	v_mov_b32_e32 v17, v4
	v_mov_b32_e32 v18, v4
	v_mov_b32_e32 v19, v4
	v_mov_b32_e32 v28, v4
	v_mov_b32_e32 v29, v4
	v_mov_b32_e32 v30, v4
	v_mov_b32_e32 v31, v4
	v_mov_b32_e32 v32, v4
	v_mov_b32_e32 v33, v4
	v_mov_b32_e32 v34, v4
	v_mov_b32_e32 v35, v4
	v_mov_b32_e32 v44, v4
	v_mov_b32_e32 v45, v4
	v_mov_b32_e32 v46, v4
	v_mov_b32_e32 v47, v4
	v_mov_b32_e32 v48, v4
	v_mov_b32_e32 v49, v4
	v_mov_b32_e32 v50, v4
	v_mov_b32_e32 v51, v4
	v_mov_b32_e32 v60, v4
	v_mov_b32_e32 v61, v4
	v_mov_b32_e32 v62, v4
	v_mov_b32_e32 v63, v4
	v_mov_b32_e32 v64, v4
	v_mov_b32_e32 v65, v4
	v_mov_b32_e32 v66, v4
	v_mov_b32_e32 v67, v4
	v_mov_b32_e32 v68, v4
	v_mov_b32_e32 v69, v4
	v_mov_b32_e32 v70, v4
	v_mov_b32_e32 v71, v4
	v_mov_b32_e32 v72, v4
	v_mov_b32_e32 v73, v4
	v_mov_b32_e32 v74, v4
	v_mov_b32_e32 v75, v4
	v_mov_b32_e32 v84, v4
	v_mov_b32_e32 v85, v4
	v_mov_b32_e32 v86, v4
	v_mov_b32_e32 v87, v4
	v_mov_b32_e32 v88, v4
	v_mov_b32_e32 v89, v4
	v_mov_b32_e32 v90, v4
	v_mov_b32_e32 v91, v4
	v_mov_b32_e32 v100, v4
	v_mov_b32_e32 v101, v4
	v_mov_b32_e32 v102, v4
	v_mov_b32_e32 v103, v4
	v_mov_b32_e32 v104, v4
	v_mov_b32_e32 v105, v4
	v_mov_b32_e32 v106, v4
	v_mov_b32_e32 v107, v4
	v_mov_b32_e32 v132, v4
	v_mov_b32_e32 v133, v4
	v_mov_b32_e32 v134, v4
	v_mov_b32_e32 v135, v4
	v_mov_b32_e32 v140, v4
	v_mov_b32_e32 v141, v4
	v_mov_b32_e32 v142, v4
	v_mov_b32_e32 v143, v4
	v_mov_b32_e32 v76, v4
	v_mov_b32_e32 v77, v4
	v_mov_b32_e32 v78, v4
	v_mov_b32_e32 v79, v4
	v_mov_b32_e32 v80, v4
	v_mov_b32_e32 v81, v4
	v_mov_b32_e32 v82, v4
	v_mov_b32_e32 v83, v4
	v_mov_b32_e32 v92, v4
	v_mov_b32_e32 v93, v4
	v_mov_b32_e32 v94, v4
	v_mov_b32_e32 v95, v4
	v_mov_b32_e32 v96, v4
	v_mov_b32_e32 v97, v4
	v_mov_b32_e32 v98, v4
	v_mov_b32_e32 v99, v4
	v_mov_b32_e32 v108, v4
	v_mov_b32_e32 v109, v4
	v_mov_b32_e32 v110, v4
	v_mov_b32_e32 v111, v4
	v_mov_b32_e32 v112, v4
	v_mov_b32_e32 v113, v4
	v_mov_b32_e32 v114, v4
	v_mov_b32_e32 v115, v4
	v_mov_b32_e32 v160, v4
	v_mov_b32_e32 v161, v4
	v_mov_b32_e32 v162, v4
	v_mov_b32_e32 v163, v4
	v_mov_b32_e32 v164, v4
	v_mov_b32_e32 v165, v4
	v_mov_b32_e32 v166, v4
	v_mov_b32_e32 v167, v4
	s_cmp_ge_u32 s24, 0x1000
	s_cbranch_scc0 .Lmy_prio_out
	s_setprio 1
